# v15: v9 + layer-1 lora-up small GEMMs: next unit's LDS-DMA tile loads issued under the current unit's epilogue (cross-instance prefetch)
# speedup vs baseline: 1.0029x; 1.0007x over previous
.LBB0_2756:
	s_cmp_gt_i32 s58, 16
	s_cselect_b64 s[2:3], -1, 0
	s_cmp_lt_i32 s59, 17
	s_cselect_b64 s[4:5], -1, 0
	s_or_b64 s[2:3], s[2:3], s[4:5]
	s_and_b64 vcc, exec, s[2:3]
	s_cbranch_vccnz .LBB0_2898
	s_waitcnt vmcnt(0)
	s_mov_b32 s101, 0
	v_mov_b32_e32 v27, 0
	s_abs_i32 s9, s56
	ds_read_b64 v[4:5], v27 offset:416
	ds_read_b64 v[2:3], v27 offset:336
	v_cvt_f32_u32_e32 v6, s9
	s_sub_i32 s11, 0, s9
	s_add_i32 s10, s56, s30
	s_waitcnt lgkmcnt(1)
	v_readfirstlane_b32 s6, v4
	v_rcp_iflag_f32_e32 v4, v6
	s_abs_i32 s5, s10
	s_lshl_b32 s4, s68, 4
	s_and_b32 s8, s4, 0x3fffffc0
	v_mul_f32_e32 v4, 0x4f7ffffe, v4
	v_cvt_u32_f32_e32 v4, v4
	s_ashr_i32 s4, s10, 31
	v_and_b32_e32 v1, 15, v0
	v_readfirstlane_b32 s7, v5
	v_readfirstlane_b32 s12, v4
	s_mul_i32 s11, s11, s12
	s_mul_hi_u32 s11, s12, s11
	s_add_i32 s11, s12, s11
	s_mul_hi_u32 s12, s5, s11
	s_mul_i32 s12, s12, s9
	s_sub_i32 s5, s5, s12
	s_sub_i32 s12, s5, s9
	s_cmp_ge_u32 s5, s9
	s_cselect_b32 s5, s12, s5
	s_sub_i32 s12, s5, s9
	s_cmp_ge_u32 s5, s9
	s_cselect_b32 s5, s12, s5
	s_xor_b32 s5, s5, s4
	s_sub_i32 s12, s5, s4
	s_waitcnt lgkmcnt(0)
	v_readfirstlane_b32 s2, v2
	v_readfirstlane_b32 s3, v3
	s_cmpk_gt_i32 s12, 0xbf
	v_or_b32_e32 v42, s8, v1
	s_cbranch_scc1 .LBB0_2761
	s_add_u32 s13, s6, 0xe128000
	s_addc_u32 s14, s7, 0
	s_add_u32 s4, s6, 0x4928000
	v_and_b32_e32 v2, 48, v0
	v_lshlrev_b32_e32 v5, 6, v42
	s_movk_i32 s18, 0x3c0
	s_addc_u32 s5, s7, 0
	v_lshl_or_b32 v3, v1, 6, v2
	v_and_or_b32 v5, v5, s18, v2
	v_lshlrev_b32_e32 v2, 2, v42
	s_add_u32 s15, s6, 0x30c8000
	v_and_b32_e32 v6, 32, v2
	v_lshlrev_b32_e32 v2, 4, v0
	s_addc_u32 s16, s7, 0
	v_lshlrev_b32_e32 v4, 2, v0
	s_lshl_b32 s17, s68, 5
	v_bitop3_b32 v2, v0, v2, 32 bitop3:0x6c
	v_lshrrev_b32_e32 v9, 3, v0
	v_lshrrev_b32_e32 v11, 1, v0
	v_and_b32_e32 v4, 32, v4
	s_and_b32 s17, s17, 0x60
	s_lshl_b32 s19, s68, 10
	v_lshrrev_b32_e32 v2, 1, v2
	v_bfe_u32 v8, v0, 2, 4
	v_or_b32_e32 v10, 64, v9
	s_movk_i32 s18, 0x70
	v_and_b32_e32 v11, 32, v11
	s_lshl_b32 s23, s17, 7
	s_lshl_b32 s24, s8, 7
	v_lshrrev_b32_e32 v7, 2, v0
	v_and_or_b32 v10, v10, s18, v8
	v_and_or_b32 v2, v2, 24, v11
	v_and_or_b32 v8, v9, 48, v8
	v_xad_u32 v5, v5, v6, 0
	v_xad_u32 v3, v3, v4, 0
	s_add_i32 s22, s19, 0
	v_lshlrev_b32_e32 v26, 8, v8
	v_lshlrev_b32_e32 v28, 8, v10
	v_mov_b32_e32 v29, v27
	v_lshlrev_b32_e32 v30, 7, v8
	v_mov_b32_e32 v31, v27
	v_lshlrev_b32_e32 v32, 7, v10
	v_mov_b32_e32 v33, v27
	v_and_or_b32 v43, v7, 12, s17
	v_add_u32_e32 v44, s8, v1
	s_lshl_b32 s17, s12, 7
	s_lshl_b32 s18, s56, 7
	v_lshlrev_b32_e32 v34, 1, v2
	v_mov_b32_e32 v35, v27
	s_add_i32 s19, s22, 0x400
	s_add_i32 s20, s22, 0x2400
	s_add_i32 s21, s22, 0x4400
	s_addk_i32 s22, 0x6400
	v_add_u32_e32 v45, s24, v5
	v_add_u32_e32 v46, s23, v3
.LBB0_2759:
	s_mul_hi_i32 s23, s12, 0x2aaaaaab
	s_lshr_b32 s24, s23, 31
	s_ashr_i32 s23, s23, 3
	s_add_i32 s23, s23, s24
	s_mul_i32 s25, s23, 0xffffe800
	s_lshl_b32 s24, s23, 7
	s_add_i32 s26, s17, s25
	s_ashr_i32 s25, s24, 31
	s_ashr_i32 s27, s26, 31
	v_or_b32_e32 v22, s24, v43
	s_lshl_b64 s[24:25], s[24:25], 7
	v_add_u32_e32 v36, s26, v44
	s_lshl_b64 s[26:27], s[26:27], 8
	s_add_u32 s26, s13, s26
	s_addc_u32 s27, s14, s27
	s_add_u32 s24, s15, s24
	v_lshl_add_u64 v[2:3], s[26:27], 0, v[26:27]
	s_mov_b32 m0, s19
	v_lshl_add_u64 v[4:5], s[26:27], 0, v[28:29]
	s_addc_u32 s25, s16, s25
	v_lshl_add_u64 v[2:3], v[2:3], 0, v[34:35]
	v_lshl_add_u64 v[4:5], v[4:5], 0, v[34:35]
	global_load_lds_dwordx4 v[2:3], off
	v_lshl_add_u64 v[2:3], s[24:25], 0, v[30:31]
	s_mov_b32 m0, s20
	v_lshl_add_u64 v[6:7], s[24:25], 0, v[32:33]
	global_load_lds_dwordx4 v[4:5], off
	v_lshl_add_u64 v[2:3], v[2:3], 0, v[34:35]
	s_mov_b32 m0, s21
	v_lshl_add_u64 v[4:5], v[6:7], 0, v[34:35]
	global_load_lds_dwordx4 v[2:3], off
	s_mov_b32 m0, s22
	v_ashrrev_i32_e32 v23, 31, v22
	global_load_lds_dwordx4 v[4:5], off
	s_waitcnt vmcnt(0)
	s_barrier
	ds_read_b128 v[18:21], v46 offset:17408
	ds_read_b128 v[14:17], v45 offset:1024
	ds_read_b128 v[48:51], v45 offset:2048
	ds_read_b128 v[6:9], v46 offset:18432
	ds_read_b128 v[10:13], v46 offset:19456
	ds_read_b128 v[2:5], v46 offset:20480
	s_waitcnt lgkmcnt(0)
	v_mfma_f32_16x16x32_bf16 v[52:55], v[18:21], v[14:17], 0
	v_lshlrev_b64 v[38:39], 2, v[22:23]
	v_lshl_add_u64 v[40:41], s[2:3], 0, v[38:39]
	global_load_dwordx4 v[200:203], v[40:41], off
	global_load_dwordx4 v[204:207], v[40:41], off offset:64
	v_ashrrev_i32_e32 v37, 31, v36
	v_mfma_f32_16x16x32_bf16 v[56:59], v[10:13], v[14:17], 0
	ds_read_b128 v[14:17], v45 offset:3072
	ds_read_b128 v[60:63], v45 offset:4096
	v_lshlrev_b64 v[88:89], 11, v[36:37]
	v_lshl_add_u64 v[88:89], s[4:5], 0, v[88:89]
	s_waitcnt lgkmcnt(0)
	v_mfma_f32_16x16x32_bf16 v[64:67], v[18:21], v[14:17], 0
	v_lshl_add_u64 v[88:89], v[88:89], 0, v[38:39]
	v_add_u32_e32 v84, 16, v36
	v_ashrrev_i32_e32 v85, 31, v84
	v_mfma_f32_16x16x32_bf16 v[68:71], v[10:13], v[14:17], 0
	ds_read_b128 v[14:17], v45 offset:5120
	ds_read_b128 v[72:75], v45 offset:6144
	v_lshlrev_b64 v[84:85], 11, v[84:85]
	v_lshl_add_u64 v[84:85], s[4:5], 0, v[84:85]
	s_waitcnt lgkmcnt(0)
	v_mfma_f32_16x16x32_bf16 v[76:79], v[18:21], v[14:17], 0
	v_lshl_add_u64 v[84:85], v[84:85], 0, v[38:39]
	v_add_u32_e32 v86, 32, v36
	v_ashrrev_i32_e32 v87, 31, v86
	v_mfma_f32_16x16x32_bf16 v[80:83], v[10:13], v[14:17], 0
	ds_read_b128 v[22:25], v45 offset:7168
	ds_read_b128 v[14:17], v45 offset:8192
	s_waitcnt lgkmcnt(0)
	s_barrier
	s_cmpk_lg_i32 s56, 0x100
	s_cbranch_scc1 .Lsgp1_own
	s_add_i32 s98, s30, 64
	s_and_b32 s98, s98, 0xff
	s_cmpk_lt_u32 s98, 0xc0
	s_cbranch_scc1 .Lsgp1_c1
	s_add_i32 s98, s30, 128
	s_and_b32 s98, s98, 0xff
	s_cmpk_lt_u32 s98, 0xc0
	s_cbranch_scc1 .Lsgp1_c2
.Lsgp1_own:
	v_lshl_add_u64 v[208:209], s[26:27], 0, v[26:27]
	v_lshl_add_u64 v[210:211], s[26:27], 0, v[28:29]
	v_lshl_add_u64 v[212:213], s[24:25], 0, v[30:31]
	v_lshl_add_u64 v[214:215], s[24:25], 0, v[32:33]
	s_mov_b32 s101, 0
	s_branch .Lsgp1_issue
.Lsgp1_c1:
	s_mul_i32 s99, s98, 1366
	s_lshr_b32 s99, s99, 16
	s_mul_i32 s100, s99, 48
	s_sub_i32 s100, s98, s100
	s_lshl_b32 s100, s100, 15
	s_add_u32 s100, s100, s6
	s_addc_u32 s101, s7, 0
	s_add_u32 s100, s100, 0xe128080
	s_addc_u32 s101, s101, 0
	v_lshl_add_u64 v[208:209], s[100:101], 0, v[26:27]
	v_lshl_add_u64 v[210:211], s[100:101], 0, v[28:29]
	s_lshl_b32 s98, s99, 14
	s_add_u32 s98, s98, s6
	s_addc_u32 s99, s7, 0
	s_add_u32 s98, s98, 0x30d8000
	s_addc_u32 s99, s99, 0
	v_lshl_add_u64 v[212:213], s[98:99], 0, v[30:31]
	v_lshl_add_u64 v[214:215], s[98:99], 0, v[32:33]
	s_mov_b32 s101, 2
	s_branch .Lsgp1_issue
.Lsgp1_c2:
	s_mul_i32 s99, s98, 1366
	s_lshr_b32 s99, s99, 16
	s_mul_i32 s100, s99, 48
	s_sub_i32 s100, s98, s100
	s_lshl_b32 s100, s100, 15
	s_add_u32 s100, s100, s6
	s_addc_u32 s101, s7, 0
	s_add_u32 s100, s100, 0xe2a8000
	s_addc_u32 s101, s101, 0
	v_lshl_add_u64 v[208:209], s[100:101], 0, v[26:27]
	v_lshl_add_u64 v[210:211], s[100:101], 0, v[28:29]
	s_lshl_b32 s98, s99, 14
	s_add_u32 s98, s98, s6
	s_addc_u32 s99, s7, 0
	s_add_u32 s98, s98, 0x30e8000
	s_addc_u32 s99, s99, 0
	v_lshl_add_u64 v[212:213], s[98:99], 0, v[30:31]
	v_lshl_add_u64 v[214:215], s[98:99], 0, v[32:33]
	s_mov_b32 s101, 3
	s_branch .Lsgp1_issue
.Lsgp1_issue:
	v_lshl_add_u64 v[208:209], v[208:209], 0, v[34:35]
	s_mov_b32 m0, s19
	s_nop 0
	global_load_lds_dwordx4 v[208:209], off
	v_lshl_add_u64 v[210:211], v[210:211], 0, v[34:35]
	s_mov_b32 m0, s20
	s_nop 0
	global_load_lds_dwordx4 v[210:211], off
	v_lshl_add_u64 v[212:213], v[212:213], 0, v[34:35]
	s_mov_b32 m0, s21
	s_nop 0
	global_load_lds_dwordx4 v[212:213], off
	v_lshl_add_u64 v[214:215], v[214:215], 0, v[34:35]
	s_mov_b32 m0, s22
	s_nop 0
	global_load_lds_dwordx4 v[214:215], off
	v_mfma_f32_16x16x32_bf16 v[52:55], v[6:9], v[48:51], v[52:55]
	v_add_u32_e32 v36, 48, v36
	s_add_i32 s12, s12, s56
	s_add_i32 s17, s17, s18
	v_mfma_f32_16x16x32_bf16 v[48:51], v[2:5], v[48:51], v[56:59]
	s_cmpk_lt_i32 s12, 0xc0
	v_mfma_f32_16x16x32_bf16 v[56:59], v[6:9], v[60:63], v[64:67]
	s_nop 2
	s_waitcnt vmcnt(4)
	s_nop 1
	v_mov_b64_e32 v[64:65], v[200:201]
	v_mov_b64_e32 v[66:67], v[202:203]
	v_mfma_f32_16x16x32_bf16 v[60:63], v[2:5], v[60:63], v[68:71]
	s_nop 0
	v_add_f32_e32 v37, v52, v64
	v_add_f32_e32 v47, v53, v65
	v_add_f32_e32 v52, v54, v66
	v_add_f32_e32 v53, v55, v67
	v_mul_f32_e32 v37, 0xbfb8aa3b, v37
	v_mul_f32_e32 v47, 0xbfb8aa3b, v47
	v_mul_f32_e32 v52, 0xbfb8aa3b, v52
	v_mul_f32_e32 v53, 0xbfb8aa3b, v53
	v_exp_f32_e32 v37, v37
	v_exp_f32_e32 v47, v47
	v_exp_f32_e32 v52, v52
	v_exp_f32_e32 v53, v53
	v_add_f32_e32 v37, 1.0, v37
	v_add_f32_e32 v47, 1.0, v47
	v_add_f32_e32 v52, 1.0, v52
	v_add_f32_e32 v53, 1.0, v53
	v_rcp_f32_e32 v37, v37
	v_rcp_f32_e32 v47, v47
	v_rcp_f32_e32 v52, v52
	v_rcp_f32_e32 v53, v53
	v_mul_f32_e32 v37, 0xbf1b4598, v37
	v_mul_f32_e32 v47, 0xbf1b4598, v47
	v_mul_f32_e32 v52, 0xbf1b4598, v52
	v_mul_f32_e32 v53, 0xbf1b4598, v53
	v_mul_f32_e32 v37, 0x3fb8aa3b, v37
	v_mul_f32_e32 v47, 0x3fb8aa3b, v47
	v_mul_f32_e32 v54, 0x3fb8aa3b, v52
	v_mul_f32_e32 v55, 0x3fb8aa3b, v53
	v_exp_f32_e32 v52, v37
	v_exp_f32_e32 v53, v47
	v_exp_f32_e32 v54, v54
	v_exp_f32_e32 v55, v55
	s_waitcnt lgkmcnt(1)
	v_mfma_f32_16x16x32_bf16 v[18:21], v[18:21], v[22:25], 0
	global_store_dwordx4 v[88:89], v[52:55], off
	s_nop 1
	v_mov_b64_e32 v[52:53], v[204:205]
	v_mov_b64_e32 v[54:55], v[206:207]
	v_mfma_f32_16x16x32_bf16 v[10:13], v[10:13], v[22:25], 0
	s_nop 0
	v_add_f32_e32 v37, v48, v52
	v_add_f32_e32 v47, v49, v53
	v_add_f32_e32 v48, v50, v54
	v_add_f32_e32 v49, v51, v55
	v_mul_f32_e32 v37, 0xbfb8aa3b, v37
	v_mul_f32_e32 v47, 0xbfb8aa3b, v47
	v_mul_f32_e32 v48, 0xbfb8aa3b, v48
	v_mul_f32_e32 v49, 0xbfb8aa3b, v49
	v_exp_f32_e32 v37, v37
	v_exp_f32_e32 v47, v47
	v_exp_f32_e32 v48, v48
	v_exp_f32_e32 v49, v49
	v_add_f32_e32 v37, 1.0, v37
	v_add_f32_e32 v47, 1.0, v47
	v_add_f32_e32 v48, 1.0, v48
	v_add_f32_e32 v49, 1.0, v49
	v_rcp_f32_e32 v37, v37
	v_rcp_f32_e32 v47, v47
	v_rcp_f32_e32 v48, v48
	v_rcp_f32_e32 v49, v49
	v_mul_f32_e32 v37, 0xbf1b4598, v37
	v_mul_f32_e32 v47, 0xbf1b4598, v47
	v_mul_f32_e32 v48, 0xbf1b4598, v48
	v_mul_f32_e32 v49, 0xbf1b4598, v49
	v_mul_f32_e32 v37, 0x3fb8aa3b, v37
	v_mul_f32_e32 v47, 0x3fb8aa3b, v47
	v_mul_f32_e32 v50, 0x3fb8aa3b, v48
	v_mul_f32_e32 v51, 0x3fb8aa3b, v49
	v_exp_f32_e32 v48, v37
	v_exp_f32_e32 v49, v47
	v_exp_f32_e32 v50, v50
	v_exp_f32_e32 v51, v51
	v_lshlrev_b64 v[52:53], 11, v[86:87]
	v_lshl_add_u64 v[52:53], s[4:5], 0, v[52:53]
	global_store_dwordx4 v[88:89], v[48:51], off offset:64
	s_nop 1
	v_mov_b64_e32 v[48:49], v[200:201]
	v_mov_b64_e32 v[50:51], v[202:203]
	s_nop 0
	v_add_f32_e32 v37, v56, v48
	v_add_f32_e32 v47, v57, v49
	v_add_f32_e32 v48, v58, v50
	v_add_f32_e32 v49, v59, v51
	v_mul_f32_e32 v37, 0xbfb8aa3b, v37
	v_mul_f32_e32 v47, 0xbfb8aa3b, v47
	v_mul_f32_e32 v48, 0xbfb8aa3b, v48
	v_mul_f32_e32 v49, 0xbfb8aa3b, v49
	v_exp_f32_e32 v37, v37
	v_exp_f32_e32 v47, v47
	v_exp_f32_e32 v48, v48
	v_exp_f32_e32 v49, v49
	v_add_f32_e32 v37, 1.0, v37
	v_add_f32_e32 v47, 1.0, v47
	v_add_f32_e32 v48, 1.0, v48
	v_add_f32_e32 v49, 1.0, v49
	v_rcp_f32_e32 v37, v37
	v_rcp_f32_e32 v47, v47
	v_rcp_f32_e32 v48, v48
	v_rcp_f32_e32 v49, v49
	v_mul_f32_e32 v37, 0xbf1b4598, v37
	v_mul_f32_e32 v47, 0xbf1b4598, v47
	v_mul_f32_e32 v48, 0xbf1b4598, v48
	v_mul_f32_e32 v49, 0xbf1b4598, v49
	v_mul_f32_e32 v37, 0x3fb8aa3b, v37
	v_mul_f32_e32 v47, 0x3fb8aa3b, v47
	v_mul_f32_e32 v50, 0x3fb8aa3b, v48
	v_mul_f32_e32 v51, 0x3fb8aa3b, v49
	v_exp_f32_e32 v48, v37
	v_exp_f32_e32 v49, v47
	v_exp_f32_e32 v50, v50
	v_exp_f32_e32 v51, v51
	v_lshl_add_u64 v[56:57], v[52:53], 0, v[38:39]
	v_mfma_f32_16x16x32_bf16 v[52:55], v[6:9], v[72:75], v[76:79]
	global_store_dwordx4 v[84:85], v[48:51], off
	s_nop 1
	v_mov_b64_e32 v[48:49], v[204:205]
	v_mov_b64_e32 v[50:51], v[206:207]
	s_waitcnt lgkmcnt(0)
	v_mfma_f32_16x16x32_bf16 v[6:9], v[6:9], v[14:17], v[18:21]
	s_nop 0
	v_add_f32_e32 v37, v60, v48
	v_add_f32_e32 v47, v61, v49
	v_add_f32_e32 v48, v62, v50
	v_add_f32_e32 v49, v63, v51
	v_mul_f32_e32 v37, 0xbfb8aa3b, v37
	v_mul_f32_e32 v47, 0xbfb8aa3b, v47
	v_mul_f32_e32 v48, 0xbfb8aa3b, v48
	v_mul_f32_e32 v49, 0xbfb8aa3b, v49
	v_exp_f32_e32 v37, v37
	v_exp_f32_e32 v47, v47
	v_exp_f32_e32 v48, v48
	v_exp_f32_e32 v49, v49
	v_add_f32_e32 v37, 1.0, v37
	v_add_f32_e32 v47, 1.0, v47
	v_add_f32_e32 v48, 1.0, v48
	v_add_f32_e32 v49, 1.0, v49
	v_rcp_f32_e32 v37, v37
	v_rcp_f32_e32 v47, v47
	v_rcp_f32_e32 v48, v48
	v_rcp_f32_e32 v49, v49
	v_mul_f32_e32 v37, 0xbf1b4598, v37
	v_mul_f32_e32 v47, 0xbf1b4598, v47
	v_mul_f32_e32 v48, 0xbf1b4598, v48
	v_mul_f32_e32 v49, 0xbf1b4598, v49
	v_mul_f32_e32 v37, 0x3fb8aa3b, v37
	v_mul_f32_e32 v47, 0x3fb8aa3b, v47
	v_mul_f32_e32 v50, 0x3fb8aa3b, v48
	v_mul_f32_e32 v51, 0x3fb8aa3b, v49
	v_exp_f32_e32 v48, v37
	v_exp_f32_e32 v49, v47
	v_exp_f32_e32 v50, v50
	v_exp_f32_e32 v51, v51
	global_store_dwordx4 v[84:85], v[48:51], off offset:64
	s_nop 1
	v_mov_b64_e32 v[48:49], v[200:201]
	v_mov_b64_e32 v[50:51], v[202:203]
	s_nop 0
	v_add_f32_e32 v37, v52, v48
	v_add_f32_e32 v47, v53, v49
	v_add_f32_e32 v48, v54, v50
	v_add_f32_e32 v49, v55, v51
	v_mul_f32_e32 v37, 0xbfb8aa3b, v37
	v_mul_f32_e32 v47, 0xbfb8aa3b, v47
	v_mul_f32_e32 v48, 0xbfb8aa3b, v48
	v_mul_f32_e32 v49, 0xbfb8aa3b, v49
	v_exp_f32_e32 v37, v37
	v_exp_f32_e32 v47, v47
	v_exp_f32_e32 v48, v48
	v_exp_f32_e32 v49, v49
	v_add_f32_e32 v37, 1.0, v37
	v_add_f32_e32 v47, 1.0, v47
	v_add_f32_e32 v48, 1.0, v48
	v_add_f32_e32 v49, 1.0, v49
	v_rcp_f32_e32 v37, v37
	v_rcp_f32_e32 v47, v47
	v_rcp_f32_e32 v48, v48
	v_rcp_f32_e32 v49, v49
	v_mul_f32_e32 v37, 0xbf1b4598, v37
	v_mul_f32_e32 v47, 0xbf1b4598, v47
	v_mul_f32_e32 v48, 0xbf1b4598, v48
	v_mul_f32_e32 v49, 0xbf1b4598, v49
	v_mul_f32_e32 v37, 0x3fb8aa3b, v37
	v_mul_f32_e32 v47, 0x3fb8aa3b, v47
	v_mul_f32_e32 v50, 0x3fb8aa3b, v48
	v_mul_f32_e32 v51, 0x3fb8aa3b, v49
	v_exp_f32_e32 v48, v37
	v_exp_f32_e32 v49, v47
	v_exp_f32_e32 v50, v50
	v_exp_f32_e32 v51, v51
	v_mfma_f32_16x16x32_bf16 v[52:55], v[2:5], v[72:75], v[80:83]
	global_store_dwordx4 v[56:57], v[48:51], off
	s_nop 1
	v_mov_b64_e32 v[48:49], v[204:205]
	v_mov_b64_e32 v[50:51], v[206:207]
	v_mfma_f32_16x16x32_bf16 v[2:5], v[2:5], v[14:17], v[10:13]
	s_nop 0
	s_nop 3
	v_add_f32_e32 v37, v52, v48
	v_add_f32_e32 v47, v53, v49
	v_add_f32_e32 v48, v54, v50
	v_add_f32_e32 v49, v55, v51
	v_mul_f32_e32 v37, 0xbfb8aa3b, v37
	v_mul_f32_e32 v47, 0xbfb8aa3b, v47
	v_mul_f32_e32 v48, 0xbfb8aa3b, v48
	v_mul_f32_e32 v49, 0xbfb8aa3b, v49
	v_exp_f32_e32 v37, v37
	v_exp_f32_e32 v47, v47
	v_exp_f32_e32 v48, v48
	v_exp_f32_e32 v49, v49
	v_add_f32_e32 v37, 1.0, v37
	v_add_f32_e32 v47, 1.0, v47
	v_add_f32_e32 v48, 1.0, v48
	v_add_f32_e32 v49, 1.0, v49
	v_rcp_f32_e32 v37, v37
	v_rcp_f32_e32 v47, v47
	v_rcp_f32_e32 v48, v48
	v_rcp_f32_e32 v49, v49
	v_mul_f32_e32 v37, 0xbf1b4598, v37
	v_mul_f32_e32 v47, 0xbf1b4598, v47
	v_mul_f32_e32 v48, 0xbf1b4598, v48
	v_mul_f32_e32 v49, 0xbf1b4598, v49
	v_mul_f32_e32 v37, 0x3fb8aa3b, v37
	v_mul_f32_e32 v47, 0x3fb8aa3b, v47
	v_mul_f32_e32 v50, 0x3fb8aa3b, v48
	v_mul_f32_e32 v51, 0x3fb8aa3b, v49
	v_exp_f32_e32 v48, v37
	v_exp_f32_e32 v49, v47
	v_exp_f32_e32 v50, v50
	v_exp_f32_e32 v51, v51
	v_ashrrev_i32_e32 v37, 31, v36
	v_lshlrev_b64 v[22:23], 11, v[36:37]
	v_lshl_add_u64 v[22:23], s[4:5], 0, v[22:23]
	global_store_dwordx4 v[56:57], v[48:51], off offset:64
	s_nop 1
	v_mov_b64_e32 v[48:49], v[200:201]
	v_mov_b64_e32 v[50:51], v[202:203]
	v_lshl_add_u64 v[22:23], v[22:23], 0, v[38:39]
	s_nop 0
	v_add_f32_e32 v6, v6, v48
	v_add_f32_e32 v7, v7, v49
	v_add_f32_e32 v8, v8, v50
	v_add_f32_e32 v9, v9, v51
	v_mul_f32_e32 v6, 0xbfb8aa3b, v6
	v_mul_f32_e32 v7, 0xbfb8aa3b, v7
	v_mul_f32_e32 v8, 0xbfb8aa3b, v8
	v_mul_f32_e32 v9, 0xbfb8aa3b, v9
	v_exp_f32_e32 v6, v6
	v_exp_f32_e32 v7, v7
	v_exp_f32_e32 v8, v8
	v_exp_f32_e32 v9, v9
	v_add_f32_e32 v6, 1.0, v6
	v_add_f32_e32 v7, 1.0, v7
	v_add_f32_e32 v8, 1.0, v8
	v_add_f32_e32 v9, 1.0, v9
	v_rcp_f32_e32 v6, v6
	v_rcp_f32_e32 v7, v7
	v_rcp_f32_e32 v8, v8
	v_rcp_f32_e32 v9, v9
	v_mul_f32_e32 v6, 0xbf1b4598, v6
	v_mul_f32_e32 v7, 0xbf1b4598, v7
	v_mul_f32_e32 v8, 0xbf1b4598, v8
	v_mul_f32_e32 v9, 0xbf1b4598, v9
	v_mul_f32_e32 v6, 0x3fb8aa3b, v6
	v_mul_f32_e32 v7, 0x3fb8aa3b, v7
	v_mul_f32_e32 v8, 0x3fb8aa3b, v8
	v_mul_f32_e32 v9, 0x3fb8aa3b, v9
	v_exp_f32_e32 v6, v6
	v_exp_f32_e32 v7, v7
	v_exp_f32_e32 v8, v8
	v_exp_f32_e32 v9, v9
	global_store_dwordx4 v[22:23], v[6:9], off
	s_nop 1
	v_mov_b64_e32 v[6:7], v[204:205]
	v_mov_b64_e32 v[8:9], v[206:207]
	s_nop 0
	v_add_f32_e32 v2, v2, v6
	v_add_f32_e32 v3, v3, v7
	v_add_f32_e32 v4, v4, v8
	v_add_f32_e32 v5, v5, v9
	v_mul_f32_e32 v2, 0xbfb8aa3b, v2
	v_mul_f32_e32 v3, 0xbfb8aa3b, v3
	v_mul_f32_e32 v4, 0xbfb8aa3b, v4
	v_mul_f32_e32 v5, 0xbfb8aa3b, v5
	v_exp_f32_e32 v2, v2
	v_exp_f32_e32 v3, v3
	v_exp_f32_e32 v4, v4
	v_exp_f32_e32 v5, v5
	v_add_f32_e32 v2, 1.0, v2
	v_add_f32_e32 v3, 1.0, v3
	v_add_f32_e32 v4, 1.0, v4
	v_add_f32_e32 v5, 1.0, v5
	v_rcp_f32_e32 v2, v2
	v_rcp_f32_e32 v3, v3
	v_rcp_f32_e32 v4, v4
	v_rcp_f32_e32 v5, v5
	v_mul_f32_e32 v2, 0xbf1b4598, v2
	v_mul_f32_e32 v3, 0xbf1b4598, v3
	v_mul_f32_e32 v4, 0xbf1b4598, v4
	v_mul_f32_e32 v5, 0xbf1b4598, v5
	v_mul_f32_e32 v2, 0x3fb8aa3b, v2
	v_mul_f32_e32 v3, 0x3fb8aa3b, v3
	v_mul_f32_e32 v4, 0x3fb8aa3b, v4
	v_mul_f32_e32 v5, 0x3fb8aa3b, v5
	v_exp_f32_e32 v2, v2
	v_exp_f32_e32 v3, v3
	v_exp_f32_e32 v4, v4
	v_exp_f32_e32 v5, v5
	global_store_dwordx4 v[22:23], v[2:5], off offset:64
	s_cbranch_scc1 .LBB0_2759
	s_nop 0
	v_mov_b32_e32 v2, 0
	ds_read_b64 v[2:3], v2 offset:336

.LBB0_2763:
	s_mul_hi_i32 s23, s12, 0x2aaaaaab
	s_lshr_b32 s24, s23, 31
	s_ashr_i32 s23, s23, 3
	s_add_i32 s23, s23, s24
	s_mul_i32 s25, s23, 0xffffe800
	s_lshl_b32 s24, s23, 7
	s_add_i32 s26, s17, s25
	s_ashr_i32 s25, s24, 31
	s_ashr_i32 s27, s26, 31
	v_or_b32_e32 v22, s24, v43
	s_lshl_b64 s[24:25], s[24:25], 7
	v_add_u32_e32 v36, s26, v44
	s_lshl_b64 s[26:27], s[26:27], 8
	s_add_u32 s26, s13, s26
	s_addc_u32 s27, s14, s27
	s_add_u32 s24, s15, s24
	v_lshl_add_u64 v[2:3], s[26:27], 0, v[26:27]
	s_mov_b32 m0, s19
	v_lshl_add_u64 v[4:5], s[26:27], 0, v[28:29]
	s_addc_u32 s25, s16, s25
	v_lshl_add_u64 v[2:3], v[2:3], 0, v[34:35]
	v_lshl_add_u64 v[4:5], v[4:5], 0, v[34:35]
	global_load_lds_dwordx4 v[2:3], off
	v_lshl_add_u64 v[2:3], s[24:25], 0, v[30:31]
	s_mov_b32 m0, s20
	v_lshl_add_u64 v[6:7], s[24:25], 0, v[32:33]
	global_load_lds_dwordx4 v[4:5], off
	v_lshl_add_u64 v[2:3], v[2:3], 0, v[34:35]
	s_mov_b32 m0, s21
	v_lshl_add_u64 v[4:5], v[6:7], 0, v[34:35]
	global_load_lds_dwordx4 v[2:3], off
	s_mov_b32 m0, s22
	v_ashrrev_i32_e32 v23, 31, v22
	global_load_lds_dwordx4 v[4:5], off
	s_cmp_eq_u32 s101, 2
	s_cbranch_scc1 .Lsgw2_pf
	s_waitcnt vmcnt(0)
	s_branch .Lsgw2_go
.Lsgw2_pf:
	s_waitcnt vmcnt(12)
.Lsgw2_go:
	s_barrier
	ds_read_b128 v[18:21], v46 offset:17408
	ds_read_b128 v[14:17], v45 offset:1024
	ds_read_b128 v[48:51], v45 offset:2048
	ds_read_b128 v[6:9], v46 offset:18432
	ds_read_b128 v[10:13], v46 offset:19456
	ds_read_b128 v[2:5], v46 offset:20480
	s_waitcnt lgkmcnt(0)
	v_mfma_f32_16x16x32_bf16 v[52:55], v[18:21], v[14:17], 0
	v_lshlrev_b64 v[38:39], 2, v[22:23]
	v_lshl_add_u64 v[40:41], s[2:3], 0, v[38:39]
	global_load_dwordx4 v[200:203], v[40:41], off offset:2048
	global_load_dwordx4 v[204:207], v[40:41], off offset:2112
	v_ashrrev_i32_e32 v37, 31, v36
	v_mfma_f32_16x16x32_bf16 v[56:59], v[10:13], v[14:17], 0
	ds_read_b128 v[14:17], v45 offset:3072
	ds_read_b128 v[60:63], v45 offset:4096
	v_lshlrev_b64 v[88:89], 11, v[36:37]
	v_lshl_add_u64 v[88:89], s[4:5], 0, v[88:89]
	s_waitcnt lgkmcnt(0)
	v_mfma_f32_16x16x32_bf16 v[64:67], v[18:21], v[14:17], 0
	v_lshl_add_u64 v[88:89], v[88:89], 0, v[38:39]
	v_add_u32_e32 v84, 16, v36
	v_ashrrev_i32_e32 v85, 31, v84
	v_mfma_f32_16x16x32_bf16 v[68:71], v[10:13], v[14:17], 0
	ds_read_b128 v[14:17], v45 offset:5120
	ds_read_b128 v[72:75], v45 offset:6144
	v_lshlrev_b64 v[84:85], 11, v[84:85]
	v_lshl_add_u64 v[84:85], s[4:5], 0, v[84:85]
	s_waitcnt lgkmcnt(0)
	v_mfma_f32_16x16x32_bf16 v[76:79], v[18:21], v[14:17], 0
	v_lshl_add_u64 v[84:85], v[84:85], 0, v[38:39]
	v_add_u32_e32 v86, 32, v36
	v_ashrrev_i32_e32 v87, 31, v86
	v_mfma_f32_16x16x32_bf16 v[80:83], v[10:13], v[14:17], 0
	ds_read_b128 v[22:25], v45 offset:7168
	ds_read_b128 v[14:17], v45 offset:8192
	s_waitcnt lgkmcnt(0)
	s_barrier
	s_cmpk_lg_i32 s56, 0x100
	s_cbranch_scc1 .Lsgp2_own
	s_add_i32 s98, s30, 128
	s_and_b32 s98, s98, 0xff
	s_cmpk_lt_u32 s98, 0xc0
	s_cbranch_scc1 .Lsgp2_c1
	s_add_i32 s98, s30, 192
	s_and_b32 s98, s98, 0xff
	s_cmpk_lt_u32 s98, 0xc0
	s_cbranch_scc1 .Lsgp2_c2

.Lsgp2_c2:
	s_mul_i32 s99, s98, 1366
	s_lshr_b32 s99, s99, 16
	s_mul_i32 s100, s99, 48
	s_sub_i32 s100, s98, s100
	s_lshl_b32 s100, s100, 15
	s_add_u32 s100, s100, s6
	s_addc_u32 s101, s7, 0
	s_add_u32 s100, s100, 0xe2a8080
	s_addc_u32 s101, s101, 0
	v_lshl_add_u64 v[208:209], s[100:101], 0, v[26:27]
	v_lshl_add_u64 v[210:211], s[100:101], 0, v[28:29]
	s_lshl_b32 s98, s99, 14
	s_add_u32 s98, s98, s6
	s_addc_u32 s99, s7, 0
	s_add_u32 s98, s98, 0x30f8000
	s_addc_u32 s99, s99, 0
	v_lshl_add_u64 v[212:213], s[98:99], 0, v[30:31]
	v_lshl_add_u64 v[214:215], s[98:99], 0, v[32:33]
	s_mov_b32 s101, 4
	s_branch .Lsgp2_issue
.Lsgp2_issue:
	v_lshl_add_u64 v[208:209], v[208:209], 0, v[34:35]
	s_mov_b32 m0, s19
	s_nop 0
	global_load_lds_dwordx4 v[208:209], off
	v_lshl_add_u64 v[210:211], v[210:211], 0, v[34:35]
	s_mov_b32 m0, s20
	s_nop 0
	global_load_lds_dwordx4 v[210:211], off
	v_lshl_add_u64 v[212:213], v[212:213], 0, v[34:35]
	s_mov_b32 m0, s21
	s_nop 0
	global_load_lds_dwordx4 v[212:213], off
	v_lshl_add_u64 v[214:215], v[214:215], 0, v[34:35]
	s_mov_b32 m0, s22
	s_nop 0
	global_load_lds_dwordx4 v[214:215], off
	v_mfma_f32_16x16x32_bf16 v[52:55], v[6:9], v[48:51], v[52:55]
	v_add_u32_e32 v36, 48, v36
	s_add_i32 s12, s12, s56
	s_add_i32 s17, s17, s18
	v_mfma_f32_16x16x32_bf16 v[48:51], v[2:5], v[48:51], v[56:59]
	s_cmpk_lt_i32 s12, 0xc0
	v_mfma_f32_16x16x32_bf16 v[56:59], v[6:9], v[60:63], v[64:67]
	s_nop 2
	s_waitcnt vmcnt(4)
	s_nop 1
	v_mov_b64_e32 v[64:65], v[200:201]
	v_mov_b64_e32 v[66:67], v[202:203]
	v_mfma_f32_16x16x32_bf16 v[60:63], v[2:5], v[60:63], v[68:71]
	s_nop 0
	v_add_f32_e32 v37, v52, v64
	v_add_f32_e32 v47, v53, v65
	v_add_f32_e32 v52, v54, v66
	v_add_f32_e32 v53, v55, v67
	v_mul_f32_e32 v37, 0xbfb8aa3b, v37
	v_mul_f32_e32 v47, 0xbfb8aa3b, v47
	v_mul_f32_e32 v52, 0xbfb8aa3b, v52
	v_mul_f32_e32 v53, 0xbfb8aa3b, v53
	v_exp_f32_e32 v37, v37
	v_exp_f32_e32 v47, v47
	v_exp_f32_e32 v52, v52
	v_exp_f32_e32 v53, v53
	v_add_f32_e32 v37, 1.0, v37
	v_add_f32_e32 v47, 1.0, v47
	v_add_f32_e32 v52, 1.0, v52
	v_add_f32_e32 v53, 1.0, v53
	v_rcp_f32_e32 v37, v37
	v_rcp_f32_e32 v47, v47
	v_rcp_f32_e32 v52, v52
	v_rcp_f32_e32 v53, v53
	v_mul_f32_e32 v37, 0xbf1b4598, v37
	v_mul_f32_e32 v47, 0xbf1b4598, v47
	v_mul_f32_e32 v52, 0xbf1b4598, v52
	v_mul_f32_e32 v53, 0xbf1b4598, v53
	v_mul_f32_e32 v37, 0x3fb8aa3b, v37
	v_mul_f32_e32 v47, 0x3fb8aa3b, v47
	v_mul_f32_e32 v54, 0x3fb8aa3b, v52
	v_mul_f32_e32 v55, 0x3fb8aa3b, v53
	v_exp_f32_e32 v52, v37
	v_exp_f32_e32 v53, v47
	v_exp_f32_e32 v54, v54
	v_exp_f32_e32 v55, v55
	s_waitcnt lgkmcnt(1)
	v_mfma_f32_16x16x32_bf16 v[18:21], v[18:21], v[22:25], 0
	global_store_dwordx4 v[88:89], v[52:55], off
	s_nop 1
	v_mov_b64_e32 v[52:53], v[204:205]
	v_mov_b64_e32 v[54:55], v[206:207]
	v_mfma_f32_16x16x32_bf16 v[10:13], v[10:13], v[22:25], 0
	s_nop 0
	v_add_f32_e32 v37, v48, v52
	v_add_f32_e32 v47, v49, v53
	v_add_f32_e32 v48, v50, v54
	v_add_f32_e32 v49, v51, v55
	v_mul_f32_e32 v37, 0xbfb8aa3b, v37
	v_mul_f32_e32 v47, 0xbfb8aa3b, v47
	v_mul_f32_e32 v48, 0xbfb8aa3b, v48
	v_mul_f32_e32 v49, 0xbfb8aa3b, v49
	v_exp_f32_e32 v37, v37
	v_exp_f32_e32 v47, v47
	v_exp_f32_e32 v48, v48
	v_exp_f32_e32 v49, v49
	v_add_f32_e32 v37, 1.0, v37
	v_add_f32_e32 v47, 1.0, v47
	v_add_f32_e32 v48, 1.0, v48
	v_add_f32_e32 v49, 1.0, v49
	v_rcp_f32_e32 v37, v37
	v_rcp_f32_e32 v47, v47
	v_rcp_f32_e32 v48, v48
	v_rcp_f32_e32 v49, v49
	v_mul_f32_e32 v37, 0xbf1b4598, v37
	v_mul_f32_e32 v47, 0xbf1b4598, v47
	v_mul_f32_e32 v48, 0xbf1b4598, v48
	v_mul_f32_e32 v49, 0xbf1b4598, v49
	v_mul_f32_e32 v37, 0x3fb8aa3b, v37
	v_mul_f32_e32 v47, 0x3fb8aa3b, v47
	v_mul_f32_e32 v50, 0x3fb8aa3b, v48
	v_mul_f32_e32 v51, 0x3fb8aa3b, v49
	v_exp_f32_e32 v48, v37
	v_exp_f32_e32 v49, v47
	v_exp_f32_e32 v50, v50
	v_exp_f32_e32 v51, v51
	v_lshlrev_b64 v[52:53], 11, v[86:87]
	v_lshl_add_u64 v[52:53], s[4:5], 0, v[52:53]
	global_store_dwordx4 v[88:89], v[48:51], off offset:64
	s_nop 1
	v_mov_b64_e32 v[48:49], v[200:201]
	v_mov_b64_e32 v[50:51], v[202:203]
	s_nop 0
	v_add_f32_e32 v37, v56, v48
	v_add_f32_e32 v47, v57, v49
	v_add_f32_e32 v48, v58, v50
	v_add_f32_e32 v49, v59, v51
	v_mul_f32_e32 v37, 0xbfb8aa3b, v37
	v_mul_f32_e32 v47, 0xbfb8aa3b, v47
	v_mul_f32_e32 v48, 0xbfb8aa3b, v48
	v_mul_f32_e32 v49, 0xbfb8aa3b, v49
	v_exp_f32_e32 v37, v37
	v_exp_f32_e32 v47, v47
	v_exp_f32_e32 v48, v48
	v_exp_f32_e32 v49, v49
	v_add_f32_e32 v37, 1.0, v37
	v_add_f32_e32 v47, 1.0, v47
	v_add_f32_e32 v48, 1.0, v48
	v_add_f32_e32 v49, 1.0, v49
	v_rcp_f32_e32 v37, v37
	v_rcp_f32_e32 v47, v47
	v_rcp_f32_e32 v48, v48
	v_rcp_f32_e32 v49, v49
	v_mul_f32_e32 v37, 0xbf1b4598, v37
	v_mul_f32_e32 v47, 0xbf1b4598, v47
	v_mul_f32_e32 v48, 0xbf1b4598, v48
	v_mul_f32_e32 v49, 0xbf1b4598, v49
	v_mul_f32_e32 v37, 0x3fb8aa3b, v37
	v_mul_f32_e32 v47, 0x3fb8aa3b, v47
	v_mul_f32_e32 v50, 0x3fb8aa3b, v48
	v_mul_f32_e32 v51, 0x3fb8aa3b, v49
	v_exp_f32_e32 v48, v37
	v_exp_f32_e32 v49, v47
	v_exp_f32_e32 v50, v50
	v_exp_f32_e32 v51, v51
	v_lshl_add_u64 v[56:57], v[52:53], 0, v[38:39]
	v_mfma_f32_16x16x32_bf16 v[52:55], v[6:9], v[72:75], v[76:79]
	global_store_dwordx4 v[84:85], v[48:51], off
	s_nop 1
	v_mov_b64_e32 v[48:49], v[204:205]
	v_mov_b64_e32 v[50:51], v[206:207]
	s_waitcnt lgkmcnt(0)
	v_mfma_f32_16x16x32_bf16 v[6:9], v[6:9], v[14:17], v[18:21]
	s_nop 0
	v_add_f32_e32 v37, v60, v48
	v_add_f32_e32 v47, v61, v49
	v_add_f32_e32 v48, v62, v50
	v_add_f32_e32 v49, v63, v51
	v_mul_f32_e32 v37, 0xbfb8aa3b, v37
	v_mul_f32_e32 v47, 0xbfb8aa3b, v47
	v_mul_f32_e32 v48, 0xbfb8aa3b, v48
	v_mul_f32_e32 v49, 0xbfb8aa3b, v49
	v_exp_f32_e32 v37, v37
	v_exp_f32_e32 v47, v47
	v_exp_f32_e32 v48, v48
	v_exp_f32_e32 v49, v49
	v_add_f32_e32 v37, 1.0, v37
	v_add_f32_e32 v47, 1.0, v47
	v_add_f32_e32 v48, 1.0, v48
	v_add_f32_e32 v49, 1.0, v49
	v_rcp_f32_e32 v37, v37
	v_rcp_f32_e32 v47, v47
	v_rcp_f32_e32 v48, v48
	v_rcp_f32_e32 v49, v49
	v_mul_f32_e32 v37, 0xbf1b4598, v37
	v_mul_f32_e32 v47, 0xbf1b4598, v47
	v_mul_f32_e32 v48, 0xbf1b4598, v48
	v_mul_f32_e32 v49, 0xbf1b4598, v49
	v_mul_f32_e32 v37, 0x3fb8aa3b, v37
	v_mul_f32_e32 v47, 0x3fb8aa3b, v47
	v_mul_f32_e32 v50, 0x3fb8aa3b, v48
	v_mul_f32_e32 v51, 0x3fb8aa3b, v49
	v_exp_f32_e32 v48, v37
	v_exp_f32_e32 v49, v47
	v_exp_f32_e32 v50, v50
	v_exp_f32_e32 v51, v51
	global_store_dwordx4 v[84:85], v[48:51], off offset:64
	s_nop 1
	v_mov_b64_e32 v[48:49], v[200:201]
	v_mov_b64_e32 v[50:51], v[202:203]
	s_nop 0
	v_add_f32_e32 v37, v52, v48
	v_add_f32_e32 v47, v53, v49
	v_add_f32_e32 v48, v54, v50
	v_add_f32_e32 v49, v55, v51
	v_mul_f32_e32 v37, 0xbfb8aa3b, v37
	v_mul_f32_e32 v47, 0xbfb8aa3b, v47
	v_mul_f32_e32 v48, 0xbfb8aa3b, v48
	v_mul_f32_e32 v49, 0xbfb8aa3b, v49
	v_exp_f32_e32 v37, v37
	v_exp_f32_e32 v47, v47
	v_exp_f32_e32 v48, v48
	v_exp_f32_e32 v49, v49
	v_add_f32_e32 v37, 1.0, v37
	v_add_f32_e32 v47, 1.0, v47
	v_add_f32_e32 v48, 1.0, v48
	v_add_f32_e32 v49, 1.0, v49
	v_rcp_f32_e32 v37, v37
	v_rcp_f32_e32 v47, v47
	v_rcp_f32_e32 v48, v48
	v_rcp_f32_e32 v49, v49
	v_mul_f32_e32 v37, 0xbf1b4598, v37
	v_mul_f32_e32 v47, 0xbf1b4598, v47
	v_mul_f32_e32 v48, 0xbf1b4598, v48
	v_mul_f32_e32 v49, 0xbf1b4598, v49
	v_mul_f32_e32 v37, 0x3fb8aa3b, v37
	v_mul_f32_e32 v47, 0x3fb8aa3b, v47
	v_mul_f32_e32 v50, 0x3fb8aa3b, v48
	v_mul_f32_e32 v51, 0x3fb8aa3b, v49
	v_exp_f32_e32 v48, v37
	v_exp_f32_e32 v49, v47
	v_exp_f32_e32 v50, v50
	v_exp_f32_e32 v51, v51
	v_mfma_f32_16x16x32_bf16 v[52:55], v[2:5], v[72:75], v[80:83]
	global_store_dwordx4 v[56:57], v[48:51], off
	s_nop 1
	v_mov_b64_e32 v[48:49], v[204:205]
	v_mov_b64_e32 v[50:51], v[206:207]
	v_mfma_f32_16x16x32_bf16 v[2:5], v[2:5], v[14:17], v[10:13]
	s_nop 0
	s_nop 3
	v_add_f32_e32 v37, v52, v48
	v_add_f32_e32 v47, v53, v49
	v_add_f32_e32 v48, v54, v50
	v_add_f32_e32 v49, v55, v51
	v_mul_f32_e32 v37, 0xbfb8aa3b, v37
	v_mul_f32_e32 v47, 0xbfb8aa3b, v47
	v_mul_f32_e32 v48, 0xbfb8aa3b, v48
	v_mul_f32_e32 v49, 0xbfb8aa3b, v49
	v_exp_f32_e32 v37, v37
	v_exp_f32_e32 v47, v47
	v_exp_f32_e32 v48, v48
	v_exp_f32_e32 v49, v49
	v_add_f32_e32 v37, 1.0, v37
	v_add_f32_e32 v47, 1.0, v47
	v_add_f32_e32 v48, 1.0, v48
	v_add_f32_e32 v49, 1.0, v49
	v_rcp_f32_e32 v37, v37
	v_rcp_f32_e32 v47, v47
	v_rcp_f32_e32 v48, v48
	v_rcp_f32_e32 v49, v49
	v_mul_f32_e32 v37, 0xbf1b4598, v37
	v_mul_f32_e32 v47, 0xbf1b4598, v47
	v_mul_f32_e32 v48, 0xbf1b4598, v48
	v_mul_f32_e32 v49, 0xbf1b4598, v49
	v_mul_f32_e32 v37, 0x3fb8aa3b, v37
	v_mul_f32_e32 v47, 0x3fb8aa3b, v47
	v_mul_f32_e32 v50, 0x3fb8aa3b, v48
	v_mul_f32_e32 v51, 0x3fb8aa3b, v49
	v_exp_f32_e32 v48, v37
	v_exp_f32_e32 v49, v47
	v_exp_f32_e32 v50, v50
	v_exp_f32_e32 v51, v51
	v_ashrrev_i32_e32 v37, 31, v36
	v_lshlrev_b64 v[22:23], 11, v[36:37]
	v_lshl_add_u64 v[22:23], s[4:5], 0, v[22:23]
	global_store_dwordx4 v[56:57], v[48:51], off offset:64
	s_nop 1
	v_mov_b64_e32 v[48:49], v[200:201]
	v_mov_b64_e32 v[50:51], v[202:203]
	v_lshl_add_u64 v[22:23], v[22:23], 0, v[38:39]
	s_nop 0
	v_add_f32_e32 v6, v6, v48
	v_add_f32_e32 v7, v7, v49
	v_add_f32_e32 v8, v8, v50
	v_add_f32_e32 v9, v9, v51
	v_mul_f32_e32 v6, 0xbfb8aa3b, v6
	v_mul_f32_e32 v7, 0xbfb8aa3b, v7
	v_mul_f32_e32 v8, 0xbfb8aa3b, v8
	v_mul_f32_e32 v9, 0xbfb8aa3b, v9
	v_exp_f32_e32 v6, v6
	v_exp_f32_e32 v7, v7
	v_exp_f32_e32 v8, v8
	v_exp_f32_e32 v9, v9
	v_add_f32_e32 v6, 1.0, v6
	v_add_f32_e32 v7, 1.0, v7
	v_add_f32_e32 v8, 1.0, v8
	v_add_f32_e32 v9, 1.0, v9
	v_rcp_f32_e32 v6, v6
	v_rcp_f32_e32 v7, v7
	v_rcp_f32_e32 v8, v8
	v_rcp_f32_e32 v9, v9
	v_mul_f32_e32 v6, 0xbf1b4598, v6
	v_mul_f32_e32 v7, 0xbf1b4598, v7
	v_mul_f32_e32 v8, 0xbf1b4598, v8
	v_mul_f32_e32 v9, 0xbf1b4598, v9
	v_mul_f32_e32 v6, 0x3fb8aa3b, v6
	v_mul_f32_e32 v7, 0x3fb8aa3b, v7
	v_mul_f32_e32 v8, 0x3fb8aa3b, v8
	v_mul_f32_e32 v9, 0x3fb8aa3b, v9
	v_exp_f32_e32 v6, v6
	v_exp_f32_e32 v7, v7
	v_exp_f32_e32 v8, v8
	v_exp_f32_e32 v9, v9
	global_store_dwordx4 v[22:23], v[6:9], off
	s_nop 1
	v_mov_b64_e32 v[6:7], v[204:205]
	v_mov_b64_e32 v[8:9], v[206:207]
	s_nop 0
	v_add_f32_e32 v2, v2, v6
	v_add_f32_e32 v3, v3, v7
	v_add_f32_e32 v4, v4, v8
	v_add_f32_e32 v5, v5, v9
	v_mul_f32_e32 v2, 0xbfb8aa3b, v2
	v_mul_f32_e32 v3, 0xbfb8aa3b, v3
	v_mul_f32_e32 v4, 0xbfb8aa3b, v4
	v_mul_f32_e32 v5, 0xbfb8aa3b, v5
	v_exp_f32_e32 v2, v2
	v_exp_f32_e32 v3, v3
	v_exp_f32_e32 v4, v4
	v_exp_f32_e32 v5, v5
	v_add_f32_e32 v2, 1.0, v2
	v_add_f32_e32 v3, 1.0, v3
	v_add_f32_e32 v4, 1.0, v4
	v_add_f32_e32 v5, 1.0, v5
	v_rcp_f32_e32 v2, v2
	v_rcp_f32_e32 v3, v3
	v_rcp_f32_e32 v4, v4
	v_rcp_f32_e32 v5, v5
	v_mul_f32_e32 v2, 0xbf1b4598, v2
	v_mul_f32_e32 v3, 0xbf1b4598, v3
	v_mul_f32_e32 v4, 0xbf1b4598, v4
	v_mul_f32_e32 v5, 0xbf1b4598, v5
	v_mul_f32_e32 v2, 0x3fb8aa3b, v2
	v_mul_f32_e32 v3, 0x3fb8aa3b, v3
	v_mul_f32_e32 v4, 0x3fb8aa3b, v4
	v_mul_f32_e32 v5, 0x3fb8aa3b, v5
	v_exp_f32_e32 v2, v2
	v_exp_f32_e32 v3, v3
	v_exp_f32_e32 v4, v4
	v_exp_f32_e32 v5, v5
	global_store_dwordx4 v[22:23], v[2:5], off offset:64
	s_cbranch_scc1 .LBB0_2763

.LBB0_2766:
	s_mul_hi_i32 s23, s12, 0x2aaaaaab
	s_lshr_b32 s24, s23, 31
	s_ashr_i32 s23, s23, 3
	s_add_i32 s23, s23, s24
	s_mul_i32 s25, s23, 0xffffe800
	s_lshl_b32 s24, s23, 7
	s_add_i32 s26, s17, s25
	s_ashr_i32 s25, s24, 31
	s_ashr_i32 s27, s26, 31
	v_or_b32_e32 v2, s24, v34
	s_lshl_b64 s[24:25], s[24:25], 7
	v_add_u32_e32 v30, s26, v35
	s_lshl_b64 s[26:27], s[26:27], 8
	s_add_u32 s26, s15, s26
	v_ashrrev_i32_e32 v3, 31, v2
	s_addc_u32 s27, s16, s27
	v_lshlrev_b64 v[28:29], 2, v[2:3]
	s_add_u32 s24, s13, s24
	v_lshl_add_u64 v[2:3], s[26:27], 0, v[18:19]
	s_mov_b32 m0, s19
	v_lshl_add_u64 v[4:5], s[26:27], 0, v[20:21]
	s_addc_u32 s25, s14, s25
	v_lshl_add_u64 v[2:3], v[2:3], 0, v[26:27]
	v_lshl_add_u64 v[4:5], v[4:5], 0, v[26:27]
	global_load_lds_dwordx4 v[2:3], off
	v_lshl_add_u64 v[2:3], s[24:25], 0, v[22:23]
	s_mov_b32 m0, s20
	v_lshl_add_u64 v[6:7], s[24:25], 0, v[24:25]
	global_load_lds_dwordx4 v[4:5], off
	v_lshl_add_u64 v[2:3], v[2:3], 0, v[26:27]
	s_mov_b32 m0, s21
	v_lshl_add_u64 v[4:5], v[6:7], 0, v[26:27]
	global_load_lds_dwordx4 v[2:3], off
	s_mov_b32 m0, s22
	v_ashrrev_i32_e32 v31, 31, v30
	global_load_lds_dwordx4 v[4:5], off
	s_cmp_eq_u32 s101, 3
	s_cbranch_scc1 .Lsgw3_pf
	s_waitcnt vmcnt(0)
	s_branch .Lsgw3_go

.Lsgw3_go:
	s_barrier
	ds_read_b128 v[38:41], v37 offset:17408
	ds_read_b128 v[6:9], v36 offset:1024
	ds_read_b128 v[44:47], v36 offset:2048
	ds_read_b128 v[10:13], v37 offset:18432
	ds_read_b128 v[14:17], v37 offset:19456
	ds_read_b128 v[2:5], v37 offset:20480
	s_waitcnt lgkmcnt(0)
	v_mfma_f32_16x16x32_bf16 v[48:51], v[38:41], v[6:9], 0
	v_lshlrev_b64 v[64:65], 11, v[30:31]
	v_lshl_add_u64 v[80:81], s[4:5], 0, v[64:65]
	v_lshl_add_u64 v[32:33], s[2:3], 0, v[28:29]
	global_load_dwordx4 v[200:203], v[32:33], off
	global_load_dwordx4 v[204:207], v[32:33], off offset:64
	v_mfma_f32_16x16x32_bf16 v[52:55], v[14:17], v[6:9], 0
	ds_read_b128 v[6:9], v36 offset:3072
	ds_read_b128 v[56:59], v36 offset:4096
	ds_read_b128 v[68:71], v36 offset:5120
	ds_read_b128 v[72:75], v36 offset:6144
	v_lshl_add_u64 v[90:91], v[80:81], 0, v[28:29]
	s_waitcnt lgkmcnt(0)
	v_mfma_f32_16x16x32_bf16 v[60:63], v[38:41], v[6:9], 0
	v_add_u32_e32 v88, 16, v30
	v_ashrrev_i32_e32 v89, 31, v88
	s_add_i32 s12, s12, s56
	v_mfma_f32_16x16x32_bf16 v[64:67], v[14:17], v[6:9], 0
	ds_read_b128 v[80:83], v36 offset:7168
	ds_read_b128 v[6:9], v36 offset:8192
	s_waitcnt lgkmcnt(0)
	s_barrier
	s_cmpk_lg_i32 s56, 0x100
	s_cbranch_scc1 .Lsgp3_own
	s_add_i32 s98, s30, 192
	s_and_b32 s98, s98, 0xff
	s_cmpk_lt_u32 s98, 0xc0
	s_cbranch_scc1 .Lsgp3_c1
.Lsgp3_own:
	v_lshl_add_u64 v[208:209], s[26:27], 0, v[18:19]
	v_lshl_add_u64 v[210:211], s[26:27], 0, v[20:21]
	v_lshl_add_u64 v[212:213], s[24:25], 0, v[22:23]
	v_lshl_add_u64 v[214:215], s[24:25], 0, v[24:25]
	s_mov_b32 s101, 0
	s_branch .Lsgp3_issue
.Lsgp3_c1:
	s_mul_i32 s99, s98, 1366
	s_lshr_b32 s99, s99, 16
	s_mul_i32 s100, s99, 48
	s_sub_i32 s100, s98, s100
	s_lshl_b32 s100, s100, 15
	s_add_u32 s100, s100, s6
	s_addc_u32 s101, s7, 0
	s_add_u32 s100, s100, 0xe2a8080
	s_addc_u32 s101, s101, 0
	v_lshl_add_u64 v[208:209], s[100:101], 0, v[18:19]
	v_lshl_add_u64 v[210:211], s[100:101], 0, v[20:21]
	s_lshl_b32 s98, s99, 14
	s_add_u32 s98, s98, s6
	s_addc_u32 s99, s7, 0
	s_add_u32 s98, s98, 0x30f8000
	s_addc_u32 s99, s99, 0
	v_lshl_add_u64 v[212:213], s[98:99], 0, v[22:23]
	v_lshl_add_u64 v[214:215], s[98:99], 0, v[24:25]
	s_mov_b32 s101, 4
	s_branch .Lsgp3_issue
.Lsgp3_issue:
	v_lshl_add_u64 v[208:209], v[208:209], 0, v[26:27]
	s_mov_b32 m0, s19
	s_nop 0
	global_load_lds_dwordx4 v[208:209], off
	v_lshl_add_u64 v[210:211], v[210:211], 0, v[26:27]
	s_mov_b32 m0, s20
	s_nop 0
	global_load_lds_dwordx4 v[210:211], off
	v_lshl_add_u64 v[212:213], v[212:213], 0, v[26:27]
	s_mov_b32 m0, s21
	s_nop 0
	global_load_lds_dwordx4 v[212:213], off
	v_lshl_add_u64 v[214:215], v[214:215], 0, v[26:27]
	s_mov_b32 m0, s22
	s_nop 0
	global_load_lds_dwordx4 v[214:215], off
	s_waitcnt vmcnt(4)
	s_nop 1
	v_mov_b64_e32 v[84:85], v[200:201]
	v_mov_b64_e32 v[86:87], v[202:203]
	v_mfma_f32_16x16x32_bf16 v[48:51], v[10:13], v[44:47], v[48:51]
	s_add_i32 s17, s17, s18
	s_cmpk_lt_i32 s12, 0xc0
	v_mfma_f32_16x16x32_bf16 v[44:47], v[2:5], v[44:47], v[52:55]
	v_mfma_f32_16x16x32_bf16 v[76:79], v[38:41], v[68:71], 0
	s_nop 0
	s_nop 2
	v_add_f32_e32 v31, v48, v84
	v_add_f32_e32 v43, v49, v85
	v_add_f32_e32 v48, v50, v86
	v_add_f32_e32 v49, v51, v87
	v_mul_f32_e32 v31, 0xbfb8aa3b, v31
	v_mul_f32_e32 v43, 0xbfb8aa3b, v43
	v_mul_f32_e32 v48, 0xbfb8aa3b, v48
	v_mul_f32_e32 v49, 0xbfb8aa3b, v49
	v_exp_f32_e32 v31, v31
	v_exp_f32_e32 v43, v43
	v_exp_f32_e32 v48, v48
	v_exp_f32_e32 v49, v49
	v_add_f32_e32 v31, 1.0, v31
	v_add_f32_e32 v43, 1.0, v43
	v_add_f32_e32 v50, 1.0, v48
	v_add_f32_e32 v51, 1.0, v49
	v_rcp_f32_e32 v48, v31
	v_rcp_f32_e32 v49, v43
	v_rcp_f32_e32 v50, v50
	v_rcp_f32_e32 v51, v51
	v_mfma_f32_16x16x32_bf16 v[68:71], v[14:17], v[68:71], 0
	global_store_dwordx4 v[90:91], v[48:51], off
	s_nop 1
	v_mov_b64_e32 v[48:49], v[204:205]
	v_mov_b64_e32 v[50:51], v[206:207]
	s_waitcnt lgkmcnt(1)
	v_mfma_f32_16x16x32_bf16 v[38:41], v[38:41], v[80:83], 0
	s_nop 0
	v_add_f32_e32 v31, v44, v48
	v_add_f32_e32 v43, v45, v49
	v_add_f32_e32 v44, v46, v50
	v_add_f32_e32 v45, v47, v51
	v_mul_f32_e32 v31, 0xbfb8aa3b, v31
	v_mul_f32_e32 v43, 0xbfb8aa3b, v43
	v_mul_f32_e32 v44, 0xbfb8aa3b, v44
	v_mul_f32_e32 v45, 0xbfb8aa3b, v45
	v_exp_f32_e32 v31, v31
	v_exp_f32_e32 v43, v43
	v_exp_f32_e32 v44, v44
	v_exp_f32_e32 v45, v45
	v_add_f32_e32 v31, 1.0, v31
	v_add_f32_e32 v43, 1.0, v43
	v_add_f32_e32 v46, 1.0, v44
	v_add_f32_e32 v47, 1.0, v45
	v_rcp_f32_e32 v44, v31
	v_rcp_f32_e32 v45, v43
	v_rcp_f32_e32 v46, v46
	v_rcp_f32_e32 v47, v47
	v_lshlrev_b64 v[48:49], 11, v[88:89]
	v_lshl_add_u64 v[48:49], s[4:5], 0, v[48:49]
	v_lshl_add_u64 v[52:53], v[48:49], 0, v[28:29]
	global_store_dwordx4 v[90:91], v[44:47], off offset:64
	s_nop 1
	v_mov_b64_e32 v[44:45], v[200:201]
	v_mov_b64_e32 v[46:47], v[202:203]
	v_mfma_f32_16x16x32_bf16 v[48:51], v[10:13], v[56:59], v[60:63]
	v_mfma_f32_16x16x32_bf16 v[14:17], v[14:17], v[80:83], 0
	s_nop 0
	s_nop 5
	v_add_f32_e32 v31, v48, v44
	v_add_f32_e32 v43, v49, v45
	v_add_f32_e32 v44, v50, v46
	v_add_f32_e32 v45, v51, v47
	v_mul_f32_e32 v31, 0xbfb8aa3b, v31
	v_mul_f32_e32 v43, 0xbfb8aa3b, v43
	v_mul_f32_e32 v44, 0xbfb8aa3b, v44
	v_mul_f32_e32 v45, 0xbfb8aa3b, v45
	v_exp_f32_e32 v31, v31
	v_exp_f32_e32 v43, v43
	v_exp_f32_e32 v44, v44
	v_exp_f32_e32 v45, v45
	v_add_f32_e32 v31, 1.0, v31
	v_add_f32_e32 v43, 1.0, v43
	v_add_f32_e32 v46, 1.0, v44
	v_add_f32_e32 v47, 1.0, v45
	v_rcp_f32_e32 v44, v31
	v_rcp_f32_e32 v45, v43
	v_rcp_f32_e32 v46, v46
	v_rcp_f32_e32 v47, v47
	v_mfma_f32_16x16x32_bf16 v[48:51], v[2:5], v[56:59], v[64:67]
	global_store_dwordx4 v[52:53], v[44:47], off
	s_nop 1
	v_mov_b64_e32 v[44:45], v[204:205]
	v_mov_b64_e32 v[46:47], v[206:207]
	s_nop 0
	s_nop 4
	v_add_f32_e32 v31, v48, v44
	v_add_f32_e32 v43, v49, v45
	v_add_f32_e32 v44, v50, v46
	v_add_f32_e32 v45, v51, v47
	v_mul_f32_e32 v31, 0xbfb8aa3b, v31
	v_mul_f32_e32 v43, 0xbfb8aa3b, v43
	v_mul_f32_e32 v44, 0xbfb8aa3b, v44
	v_mul_f32_e32 v45, 0xbfb8aa3b, v45
	v_exp_f32_e32 v31, v31
	v_exp_f32_e32 v43, v43
	v_exp_f32_e32 v44, v44
	v_exp_f32_e32 v45, v45
	v_add_f32_e32 v31, 1.0, v31
	v_add_f32_e32 v43, 1.0, v43
	v_add_f32_e32 v46, 1.0, v44
	v_add_f32_e32 v47, 1.0, v45
	v_rcp_f32_e32 v44, v31
	v_rcp_f32_e32 v45, v43
	v_rcp_f32_e32 v46, v46
	v_rcp_f32_e32 v47, v47
	v_add_u32_e32 v48, 32, v30
	v_ashrrev_i32_e32 v49, 31, v48
	v_lshlrev_b64 v[48:49], 11, v[48:49]
	global_store_dwordx4 v[52:53], v[44:47], off offset:64
	s_nop 1
	v_mov_b64_e32 v[44:45], v[200:201]
	v_mov_b64_e32 v[46:47], v[202:203]
	v_lshl_add_u64 v[48:49], s[4:5], 0, v[48:49]
	v_lshl_add_u64 v[52:53], v[48:49], 0, v[28:29]
	v_mfma_f32_16x16x32_bf16 v[48:51], v[10:13], v[72:75], v[76:79]
	v_add_u32_e32 v30, 48, v30
	s_waitcnt lgkmcnt(0)
	v_mfma_f32_16x16x32_bf16 v[10:13], v[10:13], v[6:9], v[38:41]
	s_nop 0
	s_nop 3
	v_add_f32_e32 v31, v48, v44
	v_add_f32_e32 v43, v49, v45
	v_add_f32_e32 v44, v50, v46
	v_add_f32_e32 v45, v51, v47
	v_mul_f32_e32 v31, 0xbfb8aa3b, v31
	v_mul_f32_e32 v43, 0xbfb8aa3b, v43
	v_mul_f32_e32 v44, 0xbfb8aa3b, v44
	v_mul_f32_e32 v45, 0xbfb8aa3b, v45
	v_exp_f32_e32 v31, v31
	v_exp_f32_e32 v43, v43
	v_exp_f32_e32 v44, v44
	v_exp_f32_e32 v45, v45
	v_add_f32_e32 v31, 1.0, v31
	v_add_f32_e32 v43, 1.0, v43
	v_add_f32_e32 v46, 1.0, v44
	v_add_f32_e32 v47, 1.0, v45
	v_rcp_f32_e32 v44, v31
	v_rcp_f32_e32 v45, v43
	v_rcp_f32_e32 v46, v46
	v_rcp_f32_e32 v47, v47
	v_mfma_f32_16x16x32_bf16 v[48:51], v[2:5], v[72:75], v[68:71]
	global_store_dwordx4 v[52:53], v[44:47], off
	s_nop 1
	v_mov_b64_e32 v[44:45], v[204:205]
	v_mov_b64_e32 v[46:47], v[206:207]
	v_mfma_f32_16x16x32_bf16 v[2:5], v[2:5], v[6:9], v[14:17]
	s_nop 0
	s_nop 3
	v_add_f32_e32 v31, v48, v44
	v_add_f32_e32 v43, v49, v45
	v_add_f32_e32 v44, v50, v46
	v_add_f32_e32 v45, v51, v47
	v_mul_f32_e32 v31, 0xbfb8aa3b, v31
	v_mul_f32_e32 v43, 0xbfb8aa3b, v43
	v_mul_f32_e32 v44, 0xbfb8aa3b, v44
	v_mul_f32_e32 v45, 0xbfb8aa3b, v45
	v_exp_f32_e32 v31, v31
	v_exp_f32_e32 v43, v43
	v_exp_f32_e32 v44, v44
	v_exp_f32_e32 v45, v45
	v_add_f32_e32 v31, 1.0, v31
	v_add_f32_e32 v43, 1.0, v43
	v_add_f32_e32 v46, 1.0, v44
	v_add_f32_e32 v47, 1.0, v45
	v_rcp_f32_e32 v44, v31
	v_rcp_f32_e32 v45, v43
	v_rcp_f32_e32 v46, v46
	v_rcp_f32_e32 v47, v47
	v_ashrrev_i32_e32 v31, 31, v30
	v_lshlrev_b64 v[30:31], 11, v[30:31]
	v_lshl_add_u64 v[30:31], s[4:5], 0, v[30:31]
	global_store_dwordx4 v[52:53], v[44:47], off offset:64
	s_nop 1
	v_mov_b64_e32 v[44:45], v[200:201]
	v_mov_b64_e32 v[46:47], v[202:203]
	v_lshl_add_u64 v[28:29], v[30:31], 0, v[28:29]
	s_nop 0
	v_add_f32_e32 v10, v10, v44
	v_add_f32_e32 v11, v11, v45
	v_add_f32_e32 v12, v12, v46
	v_add_f32_e32 v13, v13, v47
	v_mul_f32_e32 v10, 0xbfb8aa3b, v10
	v_mul_f32_e32 v11, 0xbfb8aa3b, v11
	v_mul_f32_e32 v12, 0xbfb8aa3b, v12
	v_mul_f32_e32 v13, 0xbfb8aa3b, v13
	v_exp_f32_e32 v10, v10
	v_exp_f32_e32 v11, v11
	v_exp_f32_e32 v12, v12
	v_exp_f32_e32 v13, v13
	v_add_f32_e32 v10, 1.0, v10
	v_add_f32_e32 v11, 1.0, v11
	v_add_f32_e32 v12, 1.0, v12
	v_add_f32_e32 v13, 1.0, v13
	v_rcp_f32_e32 v10, v10
	v_rcp_f32_e32 v11, v11
	v_rcp_f32_e32 v12, v12
	v_rcp_f32_e32 v13, v13
	global_store_dwordx4 v[28:29], v[10:13], off
	s_nop 1
	v_mov_b64_e32 v[10:11], v[204:205]
	v_mov_b64_e32 v[12:13], v[206:207]
	s_nop 0
	v_add_f32_e32 v2, v2, v10
	v_add_f32_e32 v3, v3, v11
	v_add_f32_e32 v4, v4, v12
	v_add_f32_e32 v5, v5, v13
	v_mul_f32_e32 v2, 0xbfb8aa3b, v2
	v_mul_f32_e32 v3, 0xbfb8aa3b, v3
	v_mul_f32_e32 v4, 0xbfb8aa3b, v4
	v_mul_f32_e32 v5, 0xbfb8aa3b, v5
	v_exp_f32_e32 v2, v2
	v_exp_f32_e32 v3, v3
	v_exp_f32_e32 v4, v4
	v_exp_f32_e32 v5, v5
	v_add_f32_e32 v2, 1.0, v2
	v_add_f32_e32 v3, 1.0, v3
	v_add_f32_e32 v4, 1.0, v4
	v_add_f32_e32 v5, 1.0, v5
	v_rcp_f32_e32 v2, v2
	v_rcp_f32_e32 v3, v3
	v_rcp_f32_e32 v4, v4
	v_rcp_f32_e32 v5, v5
	global_store_dwordx4 v[28:29], v[2:5], off offset:64
	s_cbranch_scc1 .LBB0_2766
	s_nop 0
	v_mov_b32_e32 v2, 0
	ds_read_b64 v[2:3], v2 offset:352

.LBB0_2770:
	s_mul_hi_i32 s23, s12, 0x2aaaaaab
	s_lshr_b32 s24, s23, 31
	s_ashr_i32 s23, s23, 3
	s_add_i32 s23, s23, s24
	s_mul_i32 s25, s23, 0xffffe800
	s_lshl_b32 s24, s23, 7
	s_add_i32 s26, s17, s25
	s_ashr_i32 s25, s24, 31
	s_ashr_i32 s27, s26, 31
	v_or_b32_e32 v2, s24, v34
	s_lshl_b64 s[24:25], s[24:25], 7
	v_add_u32_e32 v30, s26, v35
	s_lshl_b64 s[26:27], s[26:27], 8
	s_add_u32 s26, s13, s26
	v_ashrrev_i32_e32 v3, 31, v2
	s_addc_u32 s27, s14, s27
	v_lshlrev_b64 v[28:29], 2, v[2:3]
	s_add_u32 s24, s15, s24
	v_lshl_add_u64 v[2:3], s[26:27], 0, v[18:19]
	s_mov_b32 m0, s19
	v_lshl_add_u64 v[4:5], s[26:27], 0, v[20:21]
	s_addc_u32 s25, s16, s25
	v_lshl_add_u64 v[2:3], v[2:3], 0, v[26:27]
	v_lshl_add_u64 v[4:5], v[4:5], 0, v[26:27]
	global_load_lds_dwordx4 v[2:3], off
	v_lshl_add_u64 v[2:3], s[24:25], 0, v[22:23]
	s_mov_b32 m0, s20
	v_lshl_add_u64 v[6:7], s[24:25], 0, v[24:25]
	global_load_lds_dwordx4 v[4:5], off
	v_lshl_add_u64 v[2:3], v[2:3], 0, v[26:27]
	s_mov_b32 m0, s21
	v_lshl_add_u64 v[4:5], v[6:7], 0, v[26:27]
	global_load_lds_dwordx4 v[2:3], off
	s_mov_b32 m0, s22
	v_ashrrev_i32_e32 v31, 31, v30
	global_load_lds_dwordx4 v[4:5], off
	s_cmp_eq_u32 s101, 4
	s_cbranch_scc1 .Lsgw4_pf
	s_waitcnt vmcnt(0)
	s_branch .Lsgw4_go

.Lsgw4_go:
	s_barrier
	ds_read_b128 v[38:41], v37 offset:17408
	ds_read_b128 v[6:9], v36 offset:1024
	ds_read_b128 v[44:47], v36 offset:2048
	ds_read_b128 v[10:13], v37 offset:18432
	ds_read_b128 v[14:17], v37 offset:19456
	ds_read_b128 v[2:5], v37 offset:20480
	s_waitcnt lgkmcnt(0)
	v_mfma_f32_16x16x32_bf16 v[48:51], v[38:41], v[6:9], 0
	v_lshlrev_b64 v[64:65], 11, v[30:31]
	v_lshl_add_u64 v[80:81], s[4:5], 0, v[64:65]
	v_lshl_add_u64 v[32:33], s[2:3], 0, v[28:29]
	global_load_dwordx4 v[200:203], v[32:33], off offset:2048
	global_load_dwordx4 v[204:207], v[32:33], off offset:2112
	v_mfma_f32_16x16x32_bf16 v[52:55], v[14:17], v[6:9], 0
	ds_read_b128 v[6:9], v36 offset:3072
	ds_read_b128 v[56:59], v36 offset:4096
	ds_read_b128 v[68:71], v36 offset:5120
	ds_read_b128 v[72:75], v36 offset:6144
	v_lshl_add_u64 v[90:91], v[80:81], 0, v[28:29]
	s_waitcnt lgkmcnt(0)
	v_mfma_f32_16x16x32_bf16 v[60:63], v[38:41], v[6:9], 0
	v_add_u32_e32 v88, 16, v30
	v_ashrrev_i32_e32 v89, 31, v88
	s_add_i32 s12, s12, s56
	v_mfma_f32_16x16x32_bf16 v[64:67], v[14:17], v[6:9], 0
	ds_read_b128 v[80:83], v36 offset:7168
	ds_read_b128 v[6:9], v36 offset:8192
	s_waitcnt lgkmcnt(0)
	s_barrier
	s_waitcnt vmcnt(0)
	s_nop 1
	v_mov_b64_e32 v[84:85], v[200:201]
	v_mov_b64_e32 v[86:87], v[202:203]
	v_mfma_f32_16x16x32_bf16 v[48:51], v[10:13], v[44:47], v[48:51]
	s_add_i32 s17, s17, s18
	s_cmpk_lt_i32 s12, 0xc0
	v_mfma_f32_16x16x32_bf16 v[44:47], v[2:5], v[44:47], v[52:55]
	v_mfma_f32_16x16x32_bf16 v[76:79], v[38:41], v[68:71], 0
	s_nop 0
	s_nop 2
	v_add_f32_e32 v31, v48, v84
	v_add_f32_e32 v43, v49, v85
	v_add_f32_e32 v48, v50, v86
	v_add_f32_e32 v49, v51, v87
	v_mul_f32_e32 v31, 0xbfb8aa3b, v31
	v_mul_f32_e32 v43, 0xbfb8aa3b, v43
	v_mul_f32_e32 v48, 0xbfb8aa3b, v48
	v_mul_f32_e32 v49, 0xbfb8aa3b, v49
	v_exp_f32_e32 v31, v31
	v_exp_f32_e32 v43, v43
	v_exp_f32_e32 v48, v48
	v_exp_f32_e32 v49, v49
	v_add_f32_e32 v31, 1.0, v31
	v_add_f32_e32 v43, 1.0, v43
	v_add_f32_e32 v50, 1.0, v48
	v_add_f32_e32 v51, 1.0, v49
	v_rcp_f32_e32 v48, v31
	v_rcp_f32_e32 v49, v43
	v_rcp_f32_e32 v50, v50
	v_rcp_f32_e32 v51, v51
	v_mfma_f32_16x16x32_bf16 v[68:71], v[14:17], v[68:71], 0
	global_store_dwordx4 v[90:91], v[48:51], off
	s_nop 1
	v_mov_b64_e32 v[48:49], v[204:205]
	v_mov_b64_e32 v[50:51], v[206:207]
	s_waitcnt lgkmcnt(1)
	v_mfma_f32_16x16x32_bf16 v[38:41], v[38:41], v[80:83], 0
	s_nop 0
	v_add_f32_e32 v31, v44, v48
	v_add_f32_e32 v43, v45, v49
	v_add_f32_e32 v44, v46, v50
	v_add_f32_e32 v45, v47, v51
	v_mul_f32_e32 v31, 0xbfb8aa3b, v31
	v_mul_f32_e32 v43, 0xbfb8aa3b, v43
	v_mul_f32_e32 v44, 0xbfb8aa3b, v44
	v_mul_f32_e32 v45, 0xbfb8aa3b, v45
	v_exp_f32_e32 v31, v31
	v_exp_f32_e32 v43, v43
	v_exp_f32_e32 v44, v44
	v_exp_f32_e32 v45, v45
	v_add_f32_e32 v31, 1.0, v31
	v_add_f32_e32 v43, 1.0, v43
	v_add_f32_e32 v46, 1.0, v44
	v_add_f32_e32 v47, 1.0, v45
	v_rcp_f32_e32 v44, v31
	v_rcp_f32_e32 v45, v43
	v_rcp_f32_e32 v46, v46
	v_rcp_f32_e32 v47, v47
	v_lshlrev_b64 v[48:49], 11, v[88:89]
	v_lshl_add_u64 v[48:49], s[4:5], 0, v[48:49]
	v_lshl_add_u64 v[52:53], v[48:49], 0, v[28:29]
	global_store_dwordx4 v[90:91], v[44:47], off offset:64
	s_nop 1
	v_mov_b64_e32 v[44:45], v[200:201]
	v_mov_b64_e32 v[46:47], v[202:203]
	v_mfma_f32_16x16x32_bf16 v[48:51], v[10:13], v[56:59], v[60:63]
	v_mfma_f32_16x16x32_bf16 v[14:17], v[14:17], v[80:83], 0
	s_nop 0
	s_nop 5
	v_add_f32_e32 v31, v48, v44
	v_add_f32_e32 v43, v49, v45
	v_add_f32_e32 v44, v50, v46
	v_add_f32_e32 v45, v51, v47
	v_mul_f32_e32 v31, 0xbfb8aa3b, v31
	v_mul_f32_e32 v43, 0xbfb8aa3b, v43
	v_mul_f32_e32 v44, 0xbfb8aa3b, v44
	v_mul_f32_e32 v45, 0xbfb8aa3b, v45
	v_exp_f32_e32 v31, v31
	v_exp_f32_e32 v43, v43
	v_exp_f32_e32 v44, v44
	v_exp_f32_e32 v45, v45
	v_add_f32_e32 v31, 1.0, v31
	v_add_f32_e32 v43, 1.0, v43
	v_add_f32_e32 v46, 1.0, v44
	v_add_f32_e32 v47, 1.0, v45
	v_rcp_f32_e32 v44, v31
	v_rcp_f32_e32 v45, v43
	v_rcp_f32_e32 v46, v46
	v_rcp_f32_e32 v47, v47
	v_mfma_f32_16x16x32_bf16 v[48:51], v[2:5], v[56:59], v[64:67]
	global_store_dwordx4 v[52:53], v[44:47], off
	s_nop 1
	v_mov_b64_e32 v[44:45], v[204:205]
	v_mov_b64_e32 v[46:47], v[206:207]
	s_nop 0
	s_nop 4
	v_add_f32_e32 v31, v48, v44
	v_add_f32_e32 v43, v49, v45
	v_add_f32_e32 v44, v50, v46
	v_add_f32_e32 v45, v51, v47
	v_mul_f32_e32 v31, 0xbfb8aa3b, v31
	v_mul_f32_e32 v43, 0xbfb8aa3b, v43
	v_mul_f32_e32 v44, 0xbfb8aa3b, v44
	v_mul_f32_e32 v45, 0xbfb8aa3b, v45
	v_exp_f32_e32 v31, v31
	v_exp_f32_e32 v43, v43
	v_exp_f32_e32 v44, v44
	v_exp_f32_e32 v45, v45
	v_add_f32_e32 v31, 1.0, v31
	v_add_f32_e32 v43, 1.0, v43
	v_add_f32_e32 v46, 1.0, v44
	v_add_f32_e32 v47, 1.0, v45
	v_rcp_f32_e32 v44, v31
	v_rcp_f32_e32 v45, v43
	v_rcp_f32_e32 v46, v46
	v_rcp_f32_e32 v47, v47
	v_add_u32_e32 v48, 32, v30
	v_ashrrev_i32_e32 v49, 31, v48
	v_lshlrev_b64 v[48:49], 11, v[48:49]
	global_store_dwordx4 v[52:53], v[44:47], off offset:64
	s_nop 1
	v_mov_b64_e32 v[44:45], v[200:201]
	v_mov_b64_e32 v[46:47], v[202:203]
	v_lshl_add_u64 v[48:49], s[4:5], 0, v[48:49]
	v_lshl_add_u64 v[52:53], v[48:49], 0, v[28:29]
	v_mfma_f32_16x16x32_bf16 v[48:51], v[10:13], v[72:75], v[76:79]
	v_add_u32_e32 v30, 48, v30
	s_waitcnt lgkmcnt(0)
	v_mfma_f32_16x16x32_bf16 v[10:13], v[10:13], v[6:9], v[38:41]
	s_nop 0
	s_nop 3
	v_add_f32_e32 v31, v48, v44
	v_add_f32_e32 v43, v49, v45
	v_add_f32_e32 v44, v50, v46
	v_add_f32_e32 v45, v51, v47
	v_mul_f32_e32 v31, 0xbfb8aa3b, v31
	v_mul_f32_e32 v43, 0xbfb8aa3b, v43
	v_mul_f32_e32 v44, 0xbfb8aa3b, v44
	v_mul_f32_e32 v45, 0xbfb8aa3b, v45
	v_exp_f32_e32 v31, v31
	v_exp_f32_e32 v43, v43
	v_exp_f32_e32 v44, v44
	v_exp_f32_e32 v45, v45
	v_add_f32_e32 v31, 1.0, v31
	v_add_f32_e32 v43, 1.0, v43
	v_add_f32_e32 v46, 1.0, v44
	v_add_f32_e32 v47, 1.0, v45
	v_rcp_f32_e32 v44, v31
	v_rcp_f32_e32 v45, v43
	v_rcp_f32_e32 v46, v46
	v_rcp_f32_e32 v47, v47
	v_mfma_f32_16x16x32_bf16 v[48:51], v[2:5], v[72:75], v[68:71]
	global_store_dwordx4 v[52:53], v[44:47], off
	s_nop 1
	v_mov_b64_e32 v[44:45], v[204:205]
	v_mov_b64_e32 v[46:47], v[206:207]
	v_mfma_f32_16x16x32_bf16 v[2:5], v[2:5], v[6:9], v[14:17]
	s_nop 0
	s_nop 3
	v_add_f32_e32 v31, v48, v44
	v_add_f32_e32 v43, v49, v45
	v_add_f32_e32 v44, v50, v46
	v_add_f32_e32 v45, v51, v47
	v_mul_f32_e32 v31, 0xbfb8aa3b, v31
	v_mul_f32_e32 v43, 0xbfb8aa3b, v43
	v_mul_f32_e32 v44, 0xbfb8aa3b, v44
	v_mul_f32_e32 v45, 0xbfb8aa3b, v45
	v_exp_f32_e32 v31, v31
	v_exp_f32_e32 v43, v43
	v_exp_f32_e32 v44, v44
	v_exp_f32_e32 v45, v45
	v_add_f32_e32 v31, 1.0, v31
	v_add_f32_e32 v43, 1.0, v43
	v_add_f32_e32 v46, 1.0, v44
	v_add_f32_e32 v47, 1.0, v45
	v_rcp_f32_e32 v44, v31
	v_rcp_f32_e32 v45, v43
	v_rcp_f32_e32 v46, v46
	v_rcp_f32_e32 v47, v47
	v_ashrrev_i32_e32 v31, 31, v30
	v_lshlrev_b64 v[30:31], 11, v[30:31]
	v_lshl_add_u64 v[30:31], s[4:5], 0, v[30:31]
	global_store_dwordx4 v[52:53], v[44:47], off offset:64
	s_nop 1
	v_mov_b64_e32 v[44:45], v[200:201]
	v_mov_b64_e32 v[46:47], v[202:203]
	v_lshl_add_u64 v[28:29], v[30:31], 0, v[28:29]
	s_nop 0
	v_add_f32_e32 v10, v10, v44
	v_add_f32_e32 v11, v11, v45
	v_add_f32_e32 v12, v12, v46
	v_add_f32_e32 v13, v13, v47
	v_mul_f32_e32 v10, 0xbfb8aa3b, v10
	v_mul_f32_e32 v11, 0xbfb8aa3b, v11
	v_mul_f32_e32 v12, 0xbfb8aa3b, v12
	v_mul_f32_e32 v13, 0xbfb8aa3b, v13
	v_exp_f32_e32 v10, v10
	v_exp_f32_e32 v11, v11
	v_exp_f32_e32 v12, v12
	v_exp_f32_e32 v13, v13
	v_add_f32_e32 v10, 1.0, v10
	v_add_f32_e32 v11, 1.0, v11
	v_add_f32_e32 v12, 1.0, v12
	v_add_f32_e32 v13, 1.0, v13
	v_rcp_f32_e32 v10, v10
	v_rcp_f32_e32 v11, v11
	v_rcp_f32_e32 v12, v12
	v_rcp_f32_e32 v13, v13
	global_store_dwordx4 v[28:29], v[10:13], off
	s_nop 1
	v_mov_b64_e32 v[10:11], v[204:205]
	v_mov_b64_e32 v[12:13], v[206:207]
	s_nop 0
	v_add_f32_e32 v2, v2, v10
	v_add_f32_e32 v3, v3, v11
	v_add_f32_e32 v4, v4, v12
	v_add_f32_e32 v5, v5, v13
	v_mul_f32_e32 v2, 0xbfb8aa3b, v2
	v_mul_f32_e32 v3, 0xbfb8aa3b, v3
	v_mul_f32_e32 v4, 0xbfb8aa3b, v4
	v_mul_f32_e32 v5, 0xbfb8aa3b, v5
	v_exp_f32_e32 v2, v2
	v_exp_f32_e32 v3, v3
	v_exp_f32_e32 v4, v4
	v_exp_f32_e32 v5, v5
	v_add_f32_e32 v2, 1.0, v2
	v_add_f32_e32 v3, 1.0, v3
	v_add_f32_e32 v4, 1.0, v4
	v_add_f32_e32 v5, 1.0, v5
	v_rcp_f32_e32 v2, v2
	v_rcp_f32_e32 v3, v3
	v_rcp_f32_e32 v4, v4
	v_rcp_f32_e32 v5, v5
	global_store_dwordx4 v[28:29], v[2:5], off offset:64
	s_cbranch_scc1 .LBB0_2770
